# phase 0 mod_item: SiLU fill of the conditioning tile de-serialised (34 loads issued together instead of 34 load->wait trips), same arithmetic
# speedup vs baseline: 1.0113x; 1.0113x over previous
; DI float silu(float v) { return v * __builtin_amdgcn_rcpf(1.f + __builtin_amdgcn_exp2f(-1.4426950408889634f * v)); }
; DI void mod_item(const P& p, int item, char* lds) {
;     ...
;   for (int i = tid; i < 17 * 1024; i += NT) {
;     int r = i >> 10, k = i & 1023;
;     float v = r < 16 ? p.c[r * 1024 + k] : p.c_ctx[k];
;     sv[i] = silu(v);
;   }
.LBB0_970:
	v_lshlrev_b32_e32 v7, 2, v2
	s_mov_b64 s[24:25], s[54:55]
	global_load_dword v60, v7, s[24:25]
	s_add_u32 s24, s24, 0x800
	s_addc_u32 s25, s25, 0
	global_load_dword v61, v7, s[24:25]
	s_add_u32 s24, s24, 0x800
	s_addc_u32 s25, s25, 0
	global_load_dword v62, v7, s[24:25]
	s_add_u32 s24, s24, 0x800
	s_addc_u32 s25, s25, 0
	global_load_dword v63, v7, s[24:25]
	s_add_u32 s24, s24, 0x800
	s_addc_u32 s25, s25, 0
	global_load_dword v64, v7, s[24:25]
	s_add_u32 s24, s24, 0x800
	s_addc_u32 s25, s25, 0
	global_load_dword v65, v7, s[24:25]
	s_add_u32 s24, s24, 0x800
	s_addc_u32 s25, s25, 0
	global_load_dword v66, v7, s[24:25]
	s_add_u32 s24, s24, 0x800
	s_addc_u32 s25, s25, 0
	global_load_dword v67, v7, s[24:25]
	s_add_u32 s24, s24, 0x800
	s_addc_u32 s25, s25, 0
	global_load_dword v68, v7, s[24:25]
	s_add_u32 s24, s24, 0x800
	s_addc_u32 s25, s25, 0
	global_load_dword v69, v7, s[24:25]
	s_add_u32 s24, s24, 0x800
	s_addc_u32 s25, s25, 0
	global_load_dword v70, v7, s[24:25]
	s_add_u32 s24, s24, 0x800
	s_addc_u32 s25, s25, 0
	global_load_dword v71, v7, s[24:25]
	s_add_u32 s24, s24, 0x800
	s_addc_u32 s25, s25, 0
	global_load_dword v72, v7, s[24:25]
	s_add_u32 s24, s24, 0x800
	s_addc_u32 s25, s25, 0
	global_load_dword v73, v7, s[24:25]
	s_add_u32 s24, s24, 0x800
	s_addc_u32 s25, s25, 0
	global_load_dword v74, v7, s[24:25]
	s_add_u32 s24, s24, 0x800
	s_addc_u32 s25, s25, 0
	global_load_dword v75, v7, s[24:25]
	s_add_u32 s24, s24, 0x800
	s_addc_u32 s25, s25, 0
	global_load_dword v76, v7, s[24:25]
	s_add_u32 s24, s24, 0x800
	s_addc_u32 s25, s25, 0
	global_load_dword v77, v7, s[24:25]
	s_add_u32 s24, s24, 0x800
	s_addc_u32 s25, s25, 0
	global_load_dword v78, v7, s[24:25]
	s_add_u32 s24, s24, 0x800
	s_addc_u32 s25, s25, 0
	global_load_dword v79, v7, s[24:25]
	s_add_u32 s24, s24, 0x800
	s_addc_u32 s25, s25, 0
	global_load_dword v80, v7, s[24:25]
	s_add_u32 s24, s24, 0x800
	s_addc_u32 s25, s25, 0
	global_load_dword v81, v7, s[24:25]
	s_add_u32 s24, s24, 0x800
	s_addc_u32 s25, s25, 0
	global_load_dword v82, v7, s[24:25]
	s_add_u32 s24, s24, 0x800
	s_addc_u32 s25, s25, 0
	global_load_dword v83, v7, s[24:25]
	s_add_u32 s24, s24, 0x800
	s_addc_u32 s25, s25, 0
	global_load_dword v84, v7, s[24:25]
	s_add_u32 s24, s24, 0x800
	s_addc_u32 s25, s25, 0
	global_load_dword v85, v7, s[24:25]
	s_add_u32 s24, s24, 0x800
	s_addc_u32 s25, s25, 0
	global_load_dword v86, v7, s[24:25]
	s_add_u32 s24, s24, 0x800
	s_addc_u32 s25, s25, 0
	global_load_dword v87, v7, s[24:25]
	s_add_u32 s24, s24, 0x800
	s_addc_u32 s25, s25, 0
	global_load_dword v88, v7, s[24:25]
	s_add_u32 s24, s24, 0x800
	s_addc_u32 s25, s25, 0
	global_load_dword v89, v7, s[24:25]
	s_add_u32 s24, s24, 0x800
	s_addc_u32 s25, s25, 0
	global_load_dword v90, v7, s[24:25]
	s_add_u32 s24, s24, 0x800
	s_addc_u32 s25, s25, 0
	global_load_dword v91, v7, s[24:25]
	s_add_u32 s24, s24, 0x800
	s_addc_u32 s25, s25, 0
	global_load_dword v92, v7, s[58:59]
	global_load_dword v93, v7, s[58:59] offset:2048
	v_add_u32_e32 v8, 0x10000, v6
	s_waitcnt vmcnt(30)
	v_mul_f32_e32 v52, 0xbfb8aa3b, v60
	v_mul_f32_e32 v53, 0xbfb8aa3b, v61
	v_mul_f32_e32 v54, 0xbfb8aa3b, v62
	v_mul_f32_e32 v55, 0xbfb8aa3b, v63
	v_exp_f32_e32 v52, v52
	v_exp_f32_e32 v53, v53
	v_exp_f32_e32 v54, v54
	v_exp_f32_e32 v55, v55
	s_nop 0
	v_add_f32_e32 v52, 1.0, v52
	v_add_f32_e32 v53, 1.0, v53
	v_add_f32_e32 v54, 1.0, v54
	v_add_f32_e32 v55, 1.0, v55
	v_rcp_f32_e32 v52, v52
	v_rcp_f32_e32 v53, v53
	v_rcp_f32_e32 v54, v54
	v_rcp_f32_e32 v55, v55
	s_nop 0
	v_mul_f32_e32 v52, v60, v52
	v_mul_f32_e32 v53, v61, v53
	v_mul_f32_e32 v54, v62, v54
	v_mul_f32_e32 v55, v63, v55
	ds_write_b32 v6, v52 offset:0
	ds_write_b32 v6, v53 offset:2048
	ds_write_b32 v6, v54 offset:4096
	ds_write_b32 v6, v55 offset:6144
	s_waitcnt vmcnt(26)
	v_mul_f32_e32 v52, 0xbfb8aa3b, v64
	v_mul_f32_e32 v53, 0xbfb8aa3b, v65
	v_mul_f32_e32 v54, 0xbfb8aa3b, v66
	v_mul_f32_e32 v55, 0xbfb8aa3b, v67
	v_exp_f32_e32 v52, v52
	v_exp_f32_e32 v53, v53
	v_exp_f32_e32 v54, v54
	v_exp_f32_e32 v55, v55
	s_nop 0
	v_add_f32_e32 v52, 1.0, v52
	v_add_f32_e32 v53, 1.0, v53
	v_add_f32_e32 v54, 1.0, v54
	v_add_f32_e32 v55, 1.0, v55
	v_rcp_f32_e32 v52, v52
	v_rcp_f32_e32 v53, v53
	v_rcp_f32_e32 v54, v54
	v_rcp_f32_e32 v55, v55
	s_nop 0
	v_mul_f32_e32 v52, v64, v52
	v_mul_f32_e32 v53, v65, v53
	v_mul_f32_e32 v54, v66, v54
	v_mul_f32_e32 v55, v67, v55
	ds_write_b32 v6, v52 offset:8192
	ds_write_b32 v6, v53 offset:10240
	ds_write_b32 v6, v54 offset:12288
	ds_write_b32 v6, v55 offset:14336
	s_waitcnt vmcnt(22)
; DI float silu(float v) { return v * __builtin_amdgcn_rcpf(1.f + __builtin_amdgcn_exp2f(-1.4426950408889634f * v)); }
; DI void mod_item(const P& p, int item, char* lds) {
;     ...
;   for (int i = tid; i < 17 * 1024; i += NT) {
;     int r = i >> 10, k = i & 1023;
;     float v = r < 16 ? p.c[r * 1024 + k] : p.c_ctx[k];
;     sv[i] = silu(v);
;   }
	v_mul_f32_e32 v52, 0xbfb8aa3b, v68
	v_mul_f32_e32 v53, 0xbfb8aa3b, v69
	v_mul_f32_e32 v54, 0xbfb8aa3b, v70
	v_mul_f32_e32 v55, 0xbfb8aa3b, v71
	v_exp_f32_e32 v52, v52
	v_exp_f32_e32 v53, v53
	v_exp_f32_e32 v54, v54
	v_exp_f32_e32 v55, v55
	s_nop 0
	v_add_f32_e32 v52, 1.0, v52
	v_add_f32_e32 v53, 1.0, v53
	v_add_f32_e32 v54, 1.0, v54
	v_add_f32_e32 v55, 1.0, v55
	v_rcp_f32_e32 v52, v52
	v_rcp_f32_e32 v53, v53
	v_rcp_f32_e32 v54, v54
	v_rcp_f32_e32 v55, v55
	s_nop 0
	v_mul_f32_e32 v52, v68, v52
	v_mul_f32_e32 v53, v69, v53
	v_mul_f32_e32 v54, v70, v54
	v_mul_f32_e32 v55, v71, v55
	ds_write_b32 v6, v52 offset:16384
	ds_write_b32 v6, v53 offset:18432
	ds_write_b32 v6, v54 offset:20480
	ds_write_b32 v6, v55 offset:22528
	s_waitcnt vmcnt(18)
	v_mul_f32_e32 v52, 0xbfb8aa3b, v72
	v_mul_f32_e32 v53, 0xbfb8aa3b, v73
	v_mul_f32_e32 v54, 0xbfb8aa3b, v74
	v_mul_f32_e32 v55, 0xbfb8aa3b, v75
	v_exp_f32_e32 v52, v52
	v_exp_f32_e32 v53, v53
	v_exp_f32_e32 v54, v54
	v_exp_f32_e32 v55, v55
	s_nop 0
	v_add_f32_e32 v52, 1.0, v52
	v_add_f32_e32 v53, 1.0, v53
	v_add_f32_e32 v54, 1.0, v54
	v_add_f32_e32 v55, 1.0, v55
	v_rcp_f32_e32 v52, v52
	v_rcp_f32_e32 v53, v53
	v_rcp_f32_e32 v54, v54
	v_rcp_f32_e32 v55, v55
	s_nop 0
	v_mul_f32_e32 v52, v72, v52
	v_mul_f32_e32 v53, v73, v53
	v_mul_f32_e32 v54, v74, v54
	v_mul_f32_e32 v55, v75, v55
	ds_write_b32 v6, v52 offset:24576
	ds_write_b32 v6, v53 offset:26624
	ds_write_b32 v6, v54 offset:28672
	ds_write_b32 v6, v55 offset:30720
	s_waitcnt vmcnt(14)
	v_mul_f32_e32 v52, 0xbfb8aa3b, v76
	v_mul_f32_e32 v53, 0xbfb8aa3b, v77
	v_mul_f32_e32 v54, 0xbfb8aa3b, v78
	v_mul_f32_e32 v55, 0xbfb8aa3b, v79
	v_exp_f32_e32 v52, v52
	v_exp_f32_e32 v53, v53
	v_exp_f32_e32 v54, v54
	v_exp_f32_e32 v55, v55
	s_nop 0
	v_add_f32_e32 v52, 1.0, v52
	v_add_f32_e32 v53, 1.0, v53
	v_add_f32_e32 v54, 1.0, v54
	v_add_f32_e32 v55, 1.0, v55
	v_rcp_f32_e32 v52, v52
	v_rcp_f32_e32 v53, v53
	v_rcp_f32_e32 v54, v54
	v_rcp_f32_e32 v55, v55
	s_nop 0
	v_mul_f32_e32 v52, v76, v52
	v_mul_f32_e32 v53, v77, v53
	v_mul_f32_e32 v54, v78, v54
	v_mul_f32_e32 v55, v79, v55
	ds_write_b32 v6, v52 offset:32768
	ds_write_b32 v6, v53 offset:34816
	ds_write_b32 v6, v54 offset:36864
	ds_write_b32 v6, v55 offset:38912
	s_waitcnt vmcnt(10)
	v_mul_f32_e32 v52, 0xbfb8aa3b, v80
	v_mul_f32_e32 v53, 0xbfb8aa3b, v81
	v_mul_f32_e32 v54, 0xbfb8aa3b, v82
	v_mul_f32_e32 v55, 0xbfb8aa3b, v83
	v_exp_f32_e32 v52, v52
	v_exp_f32_e32 v53, v53
	v_exp_f32_e32 v54, v54
	v_exp_f32_e32 v55, v55
	s_nop 0
	v_add_f32_e32 v52, 1.0, v52
	v_add_f32_e32 v53, 1.0, v53
	v_add_f32_e32 v54, 1.0, v54
	v_add_f32_e32 v55, 1.0, v55
	v_rcp_f32_e32 v52, v52
	v_rcp_f32_e32 v53, v53
	v_rcp_f32_e32 v54, v54
	v_rcp_f32_e32 v55, v55
	s_nop 0
	v_mul_f32_e32 v52, v80, v52
	v_mul_f32_e32 v53, v81, v53
	v_mul_f32_e32 v54, v82, v54
	v_mul_f32_e32 v55, v83, v55
	ds_write_b32 v6, v52 offset:40960
	ds_write_b32 v6, v53 offset:43008
	ds_write_b32 v6, v54 offset:45056
	ds_write_b32 v6, v55 offset:47104
	s_waitcnt vmcnt(6)
	v_mul_f32_e32 v52, 0xbfb8aa3b, v84
	v_mul_f32_e32 v53, 0xbfb8aa3b, v85
	v_mul_f32_e32 v54, 0xbfb8aa3b, v86
	v_mul_f32_e32 v55, 0xbfb8aa3b, v87
	v_exp_f32_e32 v52, v52
	v_exp_f32_e32 v53, v53
	v_exp_f32_e32 v54, v54
	v_exp_f32_e32 v55, v55
	s_nop 0
	v_add_f32_e32 v52, 1.0, v52
	v_add_f32_e32 v53, 1.0, v53
	v_add_f32_e32 v54, 1.0, v54
	v_add_f32_e32 v55, 1.0, v55
	v_rcp_f32_e32 v52, v52
	v_rcp_f32_e32 v53, v53
	v_rcp_f32_e32 v54, v54
	v_rcp_f32_e32 v55, v55
	s_nop 0
	v_mul_f32_e32 v52, v84, v52
	v_mul_f32_e32 v53, v85, v53
	v_mul_f32_e32 v54, v86, v54
	v_mul_f32_e32 v55, v87, v55
	ds_write_b32 v6, v52 offset:49152
	ds_write_b32 v6, v53 offset:51200
	ds_write_b32 v6, v54 offset:53248
	ds_write_b32 v6, v55 offset:55296
	s_waitcnt vmcnt(2)
	v_mul_f32_e32 v52, 0xbfb8aa3b, v88
	v_mul_f32_e32 v53, 0xbfb8aa3b, v89
	v_mul_f32_e32 v54, 0xbfb8aa3b, v90
	v_mul_f32_e32 v55, 0xbfb8aa3b, v91
	v_exp_f32_e32 v52, v52
	v_exp_f32_e32 v53, v53
	v_exp_f32_e32 v54, v54
	v_exp_f32_e32 v55, v55
	s_nop 0
	v_add_f32_e32 v52, 1.0, v52
	v_add_f32_e32 v53, 1.0, v53
	v_add_f32_e32 v54, 1.0, v54
	v_add_f32_e32 v55, 1.0, v55
	v_rcp_f32_e32 v52, v52
	v_rcp_f32_e32 v53, v53
	v_rcp_f32_e32 v54, v54
	v_rcp_f32_e32 v55, v55
	s_nop 0
	v_mul_f32_e32 v52, v88, v52
	v_mul_f32_e32 v53, v89, v53
	v_mul_f32_e32 v54, v90, v54
	v_mul_f32_e32 v55, v91, v55
	ds_write_b32 v6, v52 offset:57344
	ds_write_b32 v6, v53 offset:59392
	ds_write_b32 v6, v54 offset:61440
	ds_write_b32 v6, v55 offset:63488
	s_waitcnt vmcnt(0)
	v_mul_f32_e32 v52, 0xbfb8aa3b, v92
	v_mul_f32_e32 v53, 0xbfb8aa3b, v93
	v_exp_f32_e32 v52, v52
	v_exp_f32_e32 v53, v53
	s_nop 0
	v_add_f32_e32 v52, 1.0, v52
	v_add_f32_e32 v53, 1.0, v53
	v_rcp_f32_e32 v52, v52
	v_rcp_f32_e32 v53, v53
	s_nop 0
	v_mul_f32_e32 v52, v92, v52
	v_mul_f32_e32 v53, v93, v53
	ds_write_b32 v8, v52 offset:0
	ds_write_b32 v8, v53 offset:2048
